# mix preamble: adaLN k-chunk partial sums restricted to the workgroup's own batch (2 passes instead of 8)
# speedup vs baseline: 1.0106x; 1.0003x over previous
.LBB0_119:
	s_or_b64 exec, exec, s[4:5]
	s_waitcnt lgkmcnt(0)
	s_barrier
	s_load_dwordx2 s[0:1], s[46:47], 0x120
	s_load_dwordx2 s[6:7], s[46:47], 0x0
	s_load_dwordx2 s[8:9], s[46:47], 0x20
	s_load_dwordx2 s[10:11], s[46:47], 0x40
	v_mov_b32_e32 v12, v214
	s_waitcnt lgkmcnt(0)
	v_mov_b32_e32 v0, s1
	v_mov_b32_e32 v1, s0
	s_movk_i32 s0, 0x1000
	s_nop 0
	v_readfirstlane_b32 s4, v1
	v_readfirstlane_b32 s5, v0
	v_cmp_gt_i32_e32 vcc, s0, v12
	v_lshlrev_b32_e32 v4, 2, v12
	s_and_saveexec_b64 s[12:13], vcc
	s_cbranch_execz .LBB0_124
	s_add_u32 s14, s4, 0xde80000
	s_addc_u32 s15, s5, 0
	s_lshr_b32 s0, s2, 6
	s_lshl_b32 s0, s0, 10
	v_add_u32_e32 v5, s0, v12
	v_lshlrev_b32_e32 v6, 2, v5
	s_mov_b64 s[16:17], 0
	s_or_b32 s0, s0, 0x1ff
